# attn_b v3: symmetric software-pipelined body, softmax VALU interleaved with PV MFMAs
# baseline (speedup 1.0000x reference)
.LBB0_641:
	s_ashr_i32 s0, s5, 7
	s_mul_i32 s23, s0, 0x3e00000
	s_mul_hi_i32 s17, s0, 0x3e00000
	s_add_u32 s0, s2, s23
	s_addc_u32 s1, s4, s17
	s_lshl_b32 s8, s5, 8
	s_and_b32 s8, s8, 0xf00
	v_and_b32_e32 v32, 15, v2
	v_lshl_add_u32 v0, v0, 5, s8
	s_waitcnt lgkmcnt(0)
	v_or_b32_e32 v3, v0, v32
	v_mov_b64_e32 v[4:5], s[0:1]
	v_mad_i64_i32 v[6:7], s[0:1], v3, s65, v[4:5]
	s_lshl_b32 s0, s5, 3
	v_or_b32_e32 v3, 16, v3
	s_and_b32 s8, s0, 0x380
	v_mad_i64_i32 v[8:9], s[0:1], v3, s65, v[4:5]
	v_ashrrev_i32_e32 v3, 3, v2
	s_waitcnt lgkmcnt(0)
	v_bfe_u32 v33, v2, 4, 2
	v_lshl_add_u64 v[6:7], v[6:7], 0, s[8:9]
	s_mov_b64 s[12:13], 0x1000
	v_lshl_add_u64 v[8:9], v[8:9], 0, s[8:9]
	v_mad_i64_i32 v[4:5], s[0:1], v3, s65, v[4:5]
	v_lshl_add_u64 v[110:111], v[6:7], 0, s[12:13]
	v_lshlrev_b32_e32 v0, 4, v33
	v_lshl_add_u64 v[108:109], v[8:9], 0, s[12:13]
	s_and_b32 s0, s5, 64
	v_lshl_add_u64 v[6:7], v[110:111], 0, v[0:1]
	v_lshl_add_u64 v[28:29], v[108:109], 0, v[0:1]
	s_lshl_b32 s8, s0, 1
	v_lshlrev_b32_e32 v0, 4, v2
	v_and_b32_e32 v0, 0x70, v0
	v_lshl_add_u64 v[4:5], v[4:5], 0, s[8:9]
	v_lshl_add_u64 v[30:31], v[4:5], 0, v[0:1]
	v_add_co_u32_e32 v4, vcc, s71, v30
	v_lshlrev_b32_e32 v118, 2, v33
	s_nop 0
	v_addc_co_u32_e32 v5, vcc, 0, v31, vcc
	global_load_dwordx4 v[20:23], v[4:5], off offset:1024
	global_load_dwordx4 v[24:27], v[4:5], off offset:1280
	global_load_dwordx4 v[16:19], v[6:7], off
	global_load_dwordx4 v[8:11], v[6:7], off offset:64
	global_load_dwordx4 v[12:15], v[28:29], off
	s_nop 0
	global_load_dwordx4 v[4:7], v[28:29], off offset:64
	v_bfe_u32 v29, v2, 2, 2
	v_lshlrev_b32_e32 v28, 3, v2
	v_or_b32_e32 v29, v118, v29
	s_mov_b64 s[18:19], 0x1400
	v_lshlrev_b32_e32 v34, 3, v33
	v_mul_lo_u32 v35, v3, s40
	v_mul_u32_u24_e32 v32, 0x50, v32
	v_and_b32_e32 v28, 24, v28
	v_mul_u32_u24_e32 v29, 0xa0, v29
	v_lshl_add_u64 v[112:113], v[30:31], 0, s[18:19]
	s_mov_b64 s[18:19], 0x1500
	s_mov_b64 s[88:89], 0x1000
	s_mov_b64 s[0:1], -1
	v_lshlrev_b32_e32 v116, 1, v32
	v_add3_u32 v119, 0, v29, v28
	s_cmp_lt_i32 s30, 4
	v_add3_u32 v120, 0, v35, v0
	v_lshl_add_u64 v[114:115], v[30:31], 0, s[18:19]
	v_lshlrev_b32_e32 v0, 1, v34
	s_barrier
	s_waitcnt vmcnt(5)
	ds_write_b128 v120, v[20:23]
	s_waitcnt vmcnt(4)
	ds_write_b128 v120, v[24:27] offset:20480
	s_waitcnt lgkmcnt(0)
	s_barrier
	s_waitcnt vmcnt(0)
	v_mov_b32_e32 v34, 0
	v_mov_b32_e32 v35, 0
	v_mov_b32_e32 v36, 0
	v_mov_b32_e32 v37, 0
	v_mov_b32_e32 v42, 0
	v_mov_b32_e32 v43, 0
	v_mov_b32_e32 v44, 0
	v_mov_b32_e32 v45, 0
	v_mov_b32_e32 v56, 0
	v_mov_b32_e32 v57, 0
	v_mov_b32_e32 v58, 0
	v_mov_b32_e32 v59, 0
	v_mov_b32_e32 v60, 0
	v_mov_b32_e32 v61, 0
	v_mov_b32_e32 v62, 0
	v_mov_b32_e32 v63, 0
	v_mov_b32_e32 v20, 0
	v_mov_b32_e32 v21, 0
	v_mov_b32_e32 v22, 0
	v_mov_b32_e32 v23, 0
	v_mov_b32_e32 v24, 0
	v_mov_b32_e32 v25, 0
	v_mov_b32_e32 v26, 0
	v_mov_b32_e32 v27, 0
	v_mov_b32_e32 v38, 0
	v_mov_b32_e32 v39, 0
	v_mov_b32_e32 v40, 0
	v_mov_b32_e32 v41, 0
	v_mov_b32_e32 v28, 0
	v_mov_b32_e32 v29, 0
	v_mov_b32_e32 v30, 0
	v_mov_b32_e32 v31, 0
	v_mov_b32_e32 v180, 0
	v_mov_b32_e32 v181, 0
	v_mov_b32_e32 v182, 0
	v_mov_b32_e32 v183, 0
	v_mov_b32_e32 v184, 0
	v_mov_b32_e32 v185, 0
	v_mov_b32_e32 v186, 0
	v_mov_b32_e32 v187, 0
	v_mov_b32_e32 v188, 0
	v_mov_b32_e32 v189, 0
	v_mov_b32_e32 v190, 0
	v_mov_b32_e32 v191, 0
	v_mov_b32_e32 v204, 0
	v_mov_b32_e32 v205, 0
	v_mov_b32_e32 v206, 0
	v_mov_b32_e32 v207, 0
	v_mov_b32_e32 v208, 0
	v_mov_b32_e32 v209, 0
	v_mov_b32_e32 v210, 0
	v_mov_b32_e32 v211, 0
	v_mov_b32_e32 v212, 0
	v_mov_b32_e32 v213, 0
	v_mov_b32_e32 v214, 0
	v_mov_b32_e32 v215, 0
	v_mov_b32_e32 v48, 0
	v_mov_b32_e32 v49, 0
	v_mov_b32_e32 v50, 0
	v_mov_b32_e32 v51, 0
	v_mov_b32_e32 v52, 0
	v_mov_b32_e32 v53, 0
	v_mov_b32_e32 v54, 0
	v_mov_b32_e32 v55, 0
	v_mov_b32_e32 v68, 0
	v_mov_b32_e32 v69, 0
	v_mov_b32_e32 v70, 0
	v_mov_b32_e32 v71, 0
	v_mov_b32_e32 v72, 0
	v_mov_b32_e32 v73, 0
	v_mov_b32_e32 v74, 0
	v_mov_b32_e32 v75, 0
	v_mov_b32_e32 v80, 0
	v_mov_b32_e32 v64, 0
	v_add_u32_e32 v137, v116, v0
	s_mov_b32 s20, 0
	s_mov_b32 s42, 0
	s_mov_b32 s43, 0
	s_mov_b32 s51, 10240
	s_mov_b32 s70, 0xf8000
	s_mov_b32 s30, 0x1f0000
	s_mov_b32 s66, 0xff800000
	s_mov_b32 s19, 0
	s_mov_b32 s18, 0xf8000
	v_lshl_add_u64 v[124:125], v[112:113], 0, s[18:19]
	global_load_dwordx4 v[124:127], v[124:125], off
	ds_read_b128 v[248:251], v137 offset:0
	ds_read_b128 v[132:135], v137 offset:64
	ds_read_b128 v[76:79], v137 offset:2560
	ds_read_b128 v[84:87], v137 offset:2624
	s_waitcnt lgkmcnt(3)
	v_mfma_f32_16x16x32_bf16 v[88:91], v[248:251], v[16:19], v[68:71]
	v_mfma_f32_16x16x32_bf16 v[104:107], v[248:251], v[12:15], v[72:75]
	ds_read_b128 v[248:251], v137 offset:5120
	s_waitcnt lgkmcnt(3)
	v_mfma_f32_16x16x32_bf16 v[88:91], v[132:135], v[8:11], v[88:91]
	v_mfma_f32_16x16x32_bf16 v[104:107], v[132:135], v[4:7], v[104:107]
	ds_read_b128 v[132:135], v137 offset:5184
	s_waitcnt lgkmcnt(3)
	v_mfma_f32_16x16x32_bf16 v[92:95], v[76:79], v[16:19], v[68:71]
	v_mfma_f32_16x16x32_bf16 v[168:171], v[76:79], v[12:15], v[72:75]
	ds_read_b128 v[76:79], v137 offset:7680
	s_waitcnt lgkmcnt(3)
	v_mfma_f32_16x16x32_bf16 v[92:95], v[84:87], v[8:11], v[92:95]
	v_mfma_f32_16x16x32_bf16 v[168:171], v[84:87], v[4:7], v[168:171]
	ds_read_b128 v[84:87], v137 offset:7744
	s_waitcnt lgkmcnt(3)
	v_mfma_f32_16x16x32_bf16 v[96:99], v[248:251], v[16:19], v[68:71]
	v_mfma_f32_16x16x32_bf16 v[172:175], v[248:251], v[12:15], v[72:75]
	s_waitcnt lgkmcnt(2)
	v_mfma_f32_16x16x32_bf16 v[96:99], v[132:135], v[8:11], v[96:99]
	v_mfma_f32_16x16x32_bf16 v[172:175], v[132:135], v[4:7], v[172:175]
	s_waitcnt lgkmcnt(1)
	v_mfma_f32_16x16x32_bf16 v[100:103], v[76:79], v[16:19], v[68:71]
	v_mfma_f32_16x16x32_bf16 v[176:179], v[76:79], v[12:15], v[72:75]
	s_waitcnt lgkmcnt(0)
	v_mfma_f32_16x16x32_bf16 v[100:103], v[84:87], v[8:11], v[100:103]
	v_mfma_f32_16x16x32_bf16 v[176:179], v[84:87], v[4:7], v[176:179]
	s_waitcnt vmcnt(0)
	ds_write_b128 v120, v[124:127] offset:10240
	s_waitcnt lgkmcnt(0)
	s_barrier
.Lb_loop:
	s_mov_b32 s67, 0
	s_mov_b32 s68, 0
	v_add_u32_e32 v122, s42, v119
	v_add_u32_e32 v136, s51, v120
	s_mov_b32 s19, 0
	s_mov_b32 s18, s30
	v_lshl_add_u64 v[124:125], v[112:113], 0, s[18:19]
	s_mov_b32 s18, s70
	v_lshl_add_u64 v[128:129], v[114:115], 0, s[18:19]
	global_load_dwordx4 v[124:127], v[124:125], off
	global_load_dwordx4 v[128:131], v[128:129], off
	ds_read_b64_tr_b16 v[248:249], v122 offset:20480
	ds_read_b64_tr_b16 v[250:251], v122 offset:23040
	ds_read_b64_tr_b16 v[132:133], v122 offset:20512
	ds_read_b64_tr_b16 v[134:135], v122 offset:23072
	ds_read_b64_tr_b16 v[76:77], v122 offset:20544
	ds_read_b64_tr_b16 v[78:79], v122 offset:23104
	v_max3_f32 v65, v88, v89, v90
	v_max3_f32 v65, v65, v91, v92
	v_max3_f32 v65, v65, v93, v94
	v_max3_f32 v65, v65, v95, v96
	v_max3_f32 v65, v65, v97, v98
	v_max3_f32 v65, v65, v99, v100
	v_max3_f32 v65, v65, v101, v102
	v_max_f32_e32 v65, v65, v103
	v_cmp_lt_f32_e32 vcc, s66, v65
	s_cbranch_vccz .Lb_nr_e_0
	v_mov_b32_e32 v66, v65
	s_nop 1
	v_permlane16_swap_b32_e32 v65, v66
	v_max_f32_e32 v65, v65, v66
	v_mov_b32_e32 v66, v65
	s_nop 1
	v_permlane32_swap_b32_e32 v65, v66
	v_max_f32_e32 v65, v65, v66
	v_cmp_lt_f32_e32 vcc, s66, v65
	s_nop 1
	v_cndmask_b32_e32 v67, 0, v65, vcc
	v_sub_f32_e32 v81, 0, v67
	v_min_f32_e32 v81, 0, v81
	v_exp_f32_e32 v81, v81
	v_sub_f32_e32 v68, v68, v67
	v_sub_f32_e32 v69, v69, v67
	v_sub_f32_e32 v70, v70, v67
	v_sub_f32_e32 v71, v71, v67
	v_mul_f32_e32 v80, v80, v81
	v_mov_b32_e32 v82, v81
	s_mov_b32 s67, 1
	v_sub_f32_e32 v88, v88, v67
	v_sub_f32_e32 v89, v89, v67
	v_sub_f32_e32 v90, v90, v67
	v_sub_f32_e32 v91, v91, v67
	v_sub_f32_e32 v92, v92, v67
	v_sub_f32_e32 v93, v93, v67
	v_sub_f32_e32 v94, v94, v67
	v_sub_f32_e32 v95, v95, v67
	v_sub_f32_e32 v96, v96, v67
	v_sub_f32_e32 v97, v97, v67
	v_sub_f32_e32 v98, v98, v67
	v_sub_f32_e32 v99, v99, v67
	v_sub_f32_e32 v100, v100, v67
	v_sub_f32_e32 v101, v101, v67
	v_sub_f32_e32 v102, v102, v67
	v_sub_f32_e32 v103, v103, v67
.Lb_nr_e_0:
	v_exp_f32_e32 v88, v88
	ds_read_b64_tr_b16 v[84:85], v122 offset:20576
	ds_read_b64_tr_b16 v[86:87], v122 offset:23136
	s_waitcnt lgkmcnt(6)
	v_mfma_f32_16x16x32_bf16 v[34:37], v[248:251], v[208:211], v[34:37]
	v_mfma_f32_16x16x32_bf16 v[20:23], v[248:251], v[212:215], v[20:23]
	v_exp_f32_e32 v89, v89
	v_exp_f32_e32 v90, v90
	v_exp_f32_e32 v91, v91
	v_exp_f32_e32 v92, v92
	v_exp_f32_e32 v93, v93
	v_exp_f32_e32 v94, v94
	v_exp_f32_e32 v95, v95
	v_exp_f32_e32 v96, v96
	v_exp_f32_e32 v97, v97
	ds_read_b64_tr_b16 v[248:249], v122 offset:25600
	ds_read_b64_tr_b16 v[250:251], v122 offset:28160
	s_waitcnt lgkmcnt(6)
	v_mfma_f32_16x16x32_bf16 v[42:45], v[132:135], v[208:211], v[42:45]
	v_mfma_f32_16x16x32_bf16 v[24:27], v[132:135], v[212:215], v[24:27]
	v_exp_f32_e32 v98, v98
	v_exp_f32_e32 v99, v99
	v_exp_f32_e32 v100, v100
	v_exp_f32_e32 v101, v101
	v_exp_f32_e32 v102, v102
	v_exp_f32_e32 v103, v103
	s_nop 0
	v_add_f32_e32 v65, v88, v89
	v_add_f32_e32 v65, v65, v90
	ds_read_b64_tr_b16 v[132:133], v122 offset:25632
	ds_read_b64_tr_b16 v[134:135], v122 offset:28192
	s_waitcnt lgkmcnt(6)
	v_mfma_f32_16x16x32_bf16 v[56:59], v[76:79], v[208:211], v[56:59]
	v_mfma_f32_16x16x32_bf16 v[38:41], v[76:79], v[212:215], v[38:41]
	v_add_f32_e32 v65, v65, v91
	v_add_f32_e32 v65, v65, v92
	v_add_f32_e32 v65, v65, v93
	v_add_f32_e32 v65, v65, v94
	v_add_f32_e32 v65, v65, v95
	v_add_f32_e32 v65, v65, v96
	v_add_f32_e32 v65, v65, v97
	v_add_f32_e32 v65, v65, v98
	v_add_f32_e32 v65, v65, v99
	ds_read_b64_tr_b16 v[76:77], v122 offset:25664
	ds_read_b64_tr_b16 v[78:79], v122 offset:28224
	s_waitcnt lgkmcnt(6)
	v_mfma_f32_16x16x32_bf16 v[60:63], v[84:87], v[208:211], v[60:63]
	v_mfma_f32_16x16x32_bf16 v[28:31], v[84:87], v[212:215], v[28:31]
	v_add_f32_e32 v65, v65, v100
	v_add_f32_e32 v65, v65, v101
	v_add_f32_e32 v65, v65, v102
	v_add_f32_e32 v65, v65, v103
	v_add_f32_e32 v80, v80, v65
	v_cvt_pk_bf16_f32 v180, v88, v89
	v_cvt_pk_bf16_f32 v181, v90, v91
	v_cvt_pk_bf16_f32 v182, v92, v93
	v_cvt_pk_bf16_f32 v183, v94, v95
	ds_read_b64_tr_b16 v[84:85], v122 offset:25696
	ds_read_b64_tr_b16 v[86:87], v122 offset:28256
	s_waitcnt lgkmcnt(6)
	v_mfma_f32_16x16x32_bf16 v[34:37], v[248:251], v[48:51], v[34:37]
	v_mfma_f32_16x16x32_bf16 v[20:23], v[248:251], v[52:55], v[20:23]
	v_cvt_pk_bf16_f32 v188, v96, v97
	v_cvt_pk_bf16_f32 v189, v98, v99
	v_cvt_pk_bf16_f32 v190, v100, v101
	v_cvt_pk_bf16_f32 v191, v102, v103
	v_max3_f32 v65, v104, v105, v106
	v_max3_f32 v65, v65, v107, v168
	v_max3_f32 v65, v65, v169, v170
	v_max3_f32 v65, v65, v171, v172
	v_max3_f32 v65, v65, v173, v174
	s_waitcnt lgkmcnt(4)
	v_mfma_f32_16x16x32_bf16 v[42:45], v[132:135], v[48:51], v[42:45]
	v_mfma_f32_16x16x32_bf16 v[24:27], v[132:135], v[52:55], v[24:27]
	v_max3_f32 v65, v65, v175, v176
	v_max3_f32 v65, v65, v177, v178
	v_max_f32_e32 v65, v65, v179
	v_cmp_lt_f32_e32 vcc, s66, v65
	s_cbranch_vccz .Lb_nr_e_1
	v_mov_b32_e32 v66, v65
	s_nop 1
	v_permlane16_swap_b32_e32 v65, v66
	v_max_f32_e32 v65, v65, v66
	v_mov_b32_e32 v66, v65
	s_nop 1
	v_permlane32_swap_b32_e32 v65, v66
	v_max_f32_e32 v65, v65, v66
	v_cmp_lt_f32_e32 vcc, s66, v65
	s_nop 1
	v_cndmask_b32_e32 v67, 0, v65, vcc
	v_sub_f32_e32 v81, 0, v67
	v_min_f32_e32 v81, 0, v81
	v_exp_f32_e32 v81, v81
	v_sub_f32_e32 v72, v72, v67
	v_sub_f32_e32 v73, v73, v67
	v_sub_f32_e32 v74, v74, v67
	v_sub_f32_e32 v75, v75, v67
	v_mul_f32_e32 v64, v64, v81
	v_mov_b32_e32 v83, v81
	s_mov_b32 s68, 1
	v_sub_f32_e32 v104, v104, v67
	v_sub_f32_e32 v105, v105, v67
	v_sub_f32_e32 v106, v106, v67
	v_sub_f32_e32 v107, v107, v67
	v_sub_f32_e32 v168, v168, v67
	v_sub_f32_e32 v169, v169, v67
	v_sub_f32_e32 v170, v170, v67
	v_sub_f32_e32 v171, v171, v67
	v_sub_f32_e32 v172, v172, v67
	v_sub_f32_e32 v173, v173, v67
	v_sub_f32_e32 v174, v174, v67
	v_sub_f32_e32 v175, v175, v67
	v_sub_f32_e32 v176, v176, v67
	v_sub_f32_e32 v177, v177, v67
	v_sub_f32_e32 v178, v178, v67
	v_sub_f32_e32 v179, v179, v67
.Lb_nr_e_1:
	v_exp_f32_e32 v104, v104
	v_exp_f32_e32 v105, v105
	v_exp_f32_e32 v106, v106
	v_exp_f32_e32 v107, v107
	v_exp_f32_e32 v168, v168
	v_exp_f32_e32 v169, v169
	s_waitcnt lgkmcnt(2)
	v_mfma_f32_16x16x32_bf16 v[56:59], v[76:79], v[48:51], v[56:59]
	v_mfma_f32_16x16x32_bf16 v[38:41], v[76:79], v[52:55], v[38:41]
	v_exp_f32_e32 v170, v170
	v_exp_f32_e32 v171, v171
	v_exp_f32_e32 v172, v172
	v_exp_f32_e32 v173, v173
	v_exp_f32_e32 v174, v174
	v_exp_f32_e32 v175, v175
	v_exp_f32_e32 v176, v176
	v_exp_f32_e32 v177, v177
	v_exp_f32_e32 v178, v178
	s_waitcnt lgkmcnt(0)
	v_mfma_f32_16x16x32_bf16 v[60:63], v[84:87], v[48:51], v[60:63]
	v_mfma_f32_16x16x32_bf16 v[28:31], v[84:87], v[52:55], v[28:31]
	v_exp_f32_e32 v179, v179
	s_cmp_eq_u32 s67, 0
	s_cbranch_scc1 .Lb_ns_e_0
	s_nop 7
	v_mul_f32_e32 v34, v34, v82
	v_mul_f32_e32 v35, v35, v82
	v_mul_f32_e32 v36, v36, v82
	v_mul_f32_e32 v37, v37, v82
	v_mul_f32_e32 v42, v42, v82
	v_mul_f32_e32 v43, v43, v82
	v_mul_f32_e32 v44, v44, v82
	v_mul_f32_e32 v45, v45, v82
	v_mul_f32_e32 v56, v56, v82
	v_mul_f32_e32 v57, v57, v82
	v_mul_f32_e32 v58, v58, v82
	v_mul_f32_e32 v59, v59, v82
	v_mul_f32_e32 v60, v60, v82
	v_mul_f32_e32 v61, v61, v82
	v_mul_f32_e32 v62, v62, v82
	v_mul_f32_e32 v63, v63, v82
.Lb_ns_e_0:
	s_cmp_eq_u32 s68, 0
	s_cbranch_scc1 .Lb_ns_e_1
	s_nop 7
	v_mul_f32_e32 v20, v20, v83
	v_mul_f32_e32 v21, v21, v83
	v_mul_f32_e32 v22, v22, v83
	v_mul_f32_e32 v23, v23, v83
	v_mul_f32_e32 v24, v24, v83
	v_mul_f32_e32 v25, v25, v83
	v_mul_f32_e32 v26, v26, v83
	v_mul_f32_e32 v27, v27, v83
	v_mul_f32_e32 v38, v38, v83
	v_mul_f32_e32 v39, v39, v83
	v_mul_f32_e32 v40, v40, v83
	v_mul_f32_e32 v41, v41, v83
	v_mul_f32_e32 v28, v28, v83
	v_mul_f32_e32 v29, v29, v83
	v_mul_f32_e32 v30, v30, v83
	v_mul_f32_e32 v31, v31, v83
.Lb_ns_e_1:
	ds_read_b128 v[248:251], v137 offset:10240
	ds_read_b128 v[132:135], v137 offset:10304
	ds_read_b128 v[76:79], v137 offset:12800
	s_nop 0
	v_add_f32_e32 v65, v104, v105
	v_add_f32_e32 v65, v65, v106
	ds_read_b128 v[84:87], v137 offset:12864
	s_waitcnt lgkmcnt(3)
	v_mfma_f32_16x16x32_bf16 v[216:219], v[248:251], v[16:19], v[68:71]
	v_mfma_f32_16x16x32_bf16 v[232:235], v[248:251], v[12:15], v[72:75]
	v_add_f32_e32 v65, v65, v107
	v_add_f32_e32 v65, v65, v168
	v_add_f32_e32 v65, v65, v169
	ds_read_b128 v[248:251], v137 offset:15360
	s_waitcnt lgkmcnt(3)
	v_mfma_f32_16x16x32_bf16 v[216:219], v[132:135], v[8:11], v[216:219]
	v_mfma_f32_16x16x32_bf16 v[232:235], v[132:135], v[4:7], v[232:235]
	v_add_f32_e32 v65, v65, v170
	v_add_f32_e32 v65, v65, v171
	v_add_f32_e32 v65, v65, v172
	ds_read_b128 v[132:135], v137 offset:15424
	s_waitcnt lgkmcnt(3)
	v_mfma_f32_16x16x32_bf16 v[220:223], v[76:79], v[16:19], v[68:71]
	v_mfma_f32_16x16x32_bf16 v[236:239], v[76:79], v[12:15], v[72:75]
	v_add_f32_e32 v65, v65, v173
	v_add_f32_e32 v65, v65, v174
	v_add_f32_e32 v65, v65, v175
	ds_read_b128 v[76:79], v137 offset:17920
	s_waitcnt lgkmcnt(3)
	v_mfma_f32_16x16x32_bf16 v[220:223], v[84:87], v[8:11], v[220:223]
	v_mfma_f32_16x16x32_bf16 v[236:239], v[84:87], v[4:7], v[236:239]
	v_add_f32_e32 v65, v65, v176
	v_add_f32_e32 v65, v65, v177
	v_add_f32_e32 v65, v65, v178
	ds_read_b128 v[84:87], v137 offset:17984
	s_waitcnt lgkmcnt(3)
	v_mfma_f32_16x16x32_bf16 v[224:227], v[248:251], v[16:19], v[68:71]
	v_mfma_f32_16x16x32_bf16 v[240:243], v[248:251], v[12:15], v[72:75]
	v_add_f32_e32 v65, v65, v179
	v_add_f32_e32 v64, v64, v65
	v_cvt_pk_bf16_f32 v184, v104, v105
	s_waitcnt lgkmcnt(2)
	v_mfma_f32_16x16x32_bf16 v[224:227], v[132:135], v[8:11], v[224:227]
	v_mfma_f32_16x16x32_bf16 v[240:243], v[132:135], v[4:7], v[240:243]
	v_cvt_pk_bf16_f32 v185, v106, v107
	v_cvt_pk_bf16_f32 v186, v168, v169
	v_cvt_pk_bf16_f32 v187, v170, v171
	s_waitcnt lgkmcnt(1)
	v_mfma_f32_16x16x32_bf16 v[228:231], v[76:79], v[16:19], v[68:71]
	v_mfma_f32_16x16x32_bf16 v[244:247], v[76:79], v[12:15], v[72:75]
	v_cvt_pk_bf16_f32 v204, v172, v173
	v_cvt_pk_bf16_f32 v205, v174, v175
	v_cvt_pk_bf16_f32 v206, v176, v177
	s_waitcnt lgkmcnt(0)
	v_mfma_f32_16x16x32_bf16 v[228:231], v[84:87], v[8:11], v[228:231]
	v_mfma_f32_16x16x32_bf16 v[244:247], v[84:87], v[4:7], v[244:247]
	v_cvt_pk_bf16_f32 v207, v178, v179
	s_waitcnt vmcnt(0)
	ds_write_b128 v120, v[124:127] offset:0
	ds_write_b128 v136, v[128:131] offset:20480
	s_mov_b32 s42, s43
	s_mov_b32 s43, s51
	s_add_i32 s51, s51, 10240
	s_cmp_lg_u32 s51, 30720
	s_cselect_b32 s51, s51, 0
	s_mov_b32 s66, 0x42800000
	s_add_i32 s20, s20, 1
	s_min_u32 s8, s20, 62
	s_add_i32 s8, s8, 1
	s_mul_i32 s70, s8, 0xf8000
	s_min_u32 s8, s20, 61
	s_add_i32 s8, s8, 2
	s_mul_i32 s30, s8, 0xf8000
	s_waitcnt lgkmcnt(0)
	s_barrier
	s_mov_b32 s67, 0
	s_mov_b32 s68, 0
	v_add_u32_e32 v122, s42, v119
	v_add_u32_e32 v136, s51, v120
	s_mov_b32 s19, 0
	s_mov_b32 s18, s30
	v_lshl_add_u64 v[124:125], v[112:113], 0, s[18:19]
	s_mov_b32 s18, s70
	v_lshl_add_u64 v[128:129], v[114:115], 0, s[18:19]
	global_load_dwordx4 v[124:127], v[124:125], off
	global_load_dwordx4 v[128:131], v[128:129], off
	ds_read_b64_tr_b16 v[248:249], v122 offset:20480
	ds_read_b64_tr_b16 v[250:251], v122 offset:23040
	ds_read_b64_tr_b16 v[132:133], v122 offset:20512
	ds_read_b64_tr_b16 v[134:135], v122 offset:23072
	ds_read_b64_tr_b16 v[76:77], v122 offset:20544
	ds_read_b64_tr_b16 v[78:79], v122 offset:23104
	v_max3_f32 v65, v216, v217, v218
	v_max3_f32 v65, v65, v219, v220
	v_max3_f32 v65, v65, v221, v222
	v_max3_f32 v65, v65, v223, v224
	v_max3_f32 v65, v65, v225, v226
	v_max3_f32 v65, v65, v227, v228
	v_max3_f32 v65, v65, v229, v230
	v_max_f32_e32 v65, v65, v231
	v_cmp_lt_f32_e32 vcc, s66, v65
	s_cbranch_vccz .Lb_nr_o_0
	v_mov_b32_e32 v66, v65
	s_nop 1
	v_permlane16_swap_b32_e32 v65, v66
	v_max_f32_e32 v65, v65, v66
	v_mov_b32_e32 v66, v65
	s_nop 1
	v_permlane32_swap_b32_e32 v65, v66
	v_max_f32_e32 v65, v65, v66
	v_cmp_lt_f32_e32 vcc, s66, v65
	s_nop 1
	v_cndmask_b32_e32 v67, 0, v65, vcc
	v_sub_f32_e32 v81, 0, v67
	v_min_f32_e32 v81, 0, v81
	v_exp_f32_e32 v81, v81
	v_sub_f32_e32 v68, v68, v67
	v_sub_f32_e32 v69, v69, v67
	v_sub_f32_e32 v70, v70, v67
	v_sub_f32_e32 v71, v71, v67
	v_mul_f32_e32 v80, v80, v81
	v_mov_b32_e32 v82, v81
	s_mov_b32 s67, 1
	v_sub_f32_e32 v216, v216, v67
	v_sub_f32_e32 v217, v217, v67
	v_sub_f32_e32 v218, v218, v67
	v_sub_f32_e32 v219, v219, v67
	v_sub_f32_e32 v220, v220, v67
	v_sub_f32_e32 v221, v221, v67
	v_sub_f32_e32 v222, v222, v67
	v_sub_f32_e32 v223, v223, v67
	v_sub_f32_e32 v224, v224, v67
	v_sub_f32_e32 v225, v225, v67
	v_sub_f32_e32 v226, v226, v67
	v_sub_f32_e32 v227, v227, v67
	v_sub_f32_e32 v228, v228, v67
	v_sub_f32_e32 v229, v229, v67
	v_sub_f32_e32 v230, v230, v67
	v_sub_f32_e32 v231, v231, v67
.Lb_nr_o_0:
	v_exp_f32_e32 v216, v216
	ds_read_b64_tr_b16 v[84:85], v122 offset:20576
	ds_read_b64_tr_b16 v[86:87], v122 offset:23136
	s_waitcnt lgkmcnt(6)
	v_mfma_f32_16x16x32_bf16 v[34:37], v[248:251], v[180:183], v[34:37]
	v_mfma_f32_16x16x32_bf16 v[20:23], v[248:251], v[184:187], v[20:23]
	v_exp_f32_e32 v217, v217
	v_exp_f32_e32 v218, v218
	v_exp_f32_e32 v219, v219
	v_exp_f32_e32 v220, v220
	v_exp_f32_e32 v221, v221
	v_exp_f32_e32 v222, v222
	v_exp_f32_e32 v223, v223
	v_exp_f32_e32 v224, v224
	v_exp_f32_e32 v225, v225
	ds_read_b64_tr_b16 v[248:249], v122 offset:25600
	ds_read_b64_tr_b16 v[250:251], v122 offset:28160
	s_waitcnt lgkmcnt(6)
	v_mfma_f32_16x16x32_bf16 v[42:45], v[132:135], v[180:183], v[42:45]
	v_mfma_f32_16x16x32_bf16 v[24:27], v[132:135], v[184:187], v[24:27]
	v_exp_f32_e32 v226, v226
	v_exp_f32_e32 v227, v227
	v_exp_f32_e32 v228, v228
	v_exp_f32_e32 v229, v229
	v_exp_f32_e32 v230, v230
	v_exp_f32_e32 v231, v231
	s_nop 0
	v_add_f32_e32 v65, v216, v217
	v_add_f32_e32 v65, v65, v218
	ds_read_b64_tr_b16 v[132:133], v122 offset:25632
	ds_read_b64_tr_b16 v[134:135], v122 offset:28192
	s_waitcnt lgkmcnt(6)
	v_mfma_f32_16x16x32_bf16 v[56:59], v[76:79], v[180:183], v[56:59]
	v_mfma_f32_16x16x32_bf16 v[38:41], v[76:79], v[184:187], v[38:41]
	v_add_f32_e32 v65, v65, v219
	v_add_f32_e32 v65, v65, v220
	v_add_f32_e32 v65, v65, v221
	v_add_f32_e32 v65, v65, v222
	v_add_f32_e32 v65, v65, v223
	v_add_f32_e32 v65, v65, v224
	v_add_f32_e32 v65, v65, v225
	v_add_f32_e32 v65, v65, v226
	v_add_f32_e32 v65, v65, v227
	ds_read_b64_tr_b16 v[76:77], v122 offset:25664
	ds_read_b64_tr_b16 v[78:79], v122 offset:28224
	s_waitcnt lgkmcnt(6)
	v_mfma_f32_16x16x32_bf16 v[60:63], v[84:87], v[180:183], v[60:63]
	v_mfma_f32_16x16x32_bf16 v[28:31], v[84:87], v[184:187], v[28:31]
	v_add_f32_e32 v65, v65, v228
	v_add_f32_e32 v65, v65, v229
	v_add_f32_e32 v65, v65, v230
	v_add_f32_e32 v65, v65, v231
	v_add_f32_e32 v80, v80, v65
	v_cvt_pk_bf16_f32 v208, v216, v217
	v_cvt_pk_bf16_f32 v209, v218, v219
	v_cvt_pk_bf16_f32 v210, v220, v221
	v_cvt_pk_bf16_f32 v211, v222, v223
	ds_read_b64_tr_b16 v[84:85], v122 offset:25696
	ds_read_b64_tr_b16 v[86:87], v122 offset:28256
	s_waitcnt lgkmcnt(6)
	v_mfma_f32_16x16x32_bf16 v[34:37], v[248:251], v[188:191], v[34:37]
	v_mfma_f32_16x16x32_bf16 v[20:23], v[248:251], v[204:207], v[20:23]
	v_cvt_pk_bf16_f32 v48, v224, v225
	v_cvt_pk_bf16_f32 v49, v226, v227
	v_cvt_pk_bf16_f32 v50, v228, v229
	v_cvt_pk_bf16_f32 v51, v230, v231
	v_max3_f32 v65, v232, v233, v234
	v_max3_f32 v65, v65, v235, v236
	v_max3_f32 v65, v65, v237, v238
	v_max3_f32 v65, v65, v239, v240
	v_max3_f32 v65, v65, v241, v242
	s_waitcnt lgkmcnt(4)
	v_mfma_f32_16x16x32_bf16 v[42:45], v[132:135], v[188:191], v[42:45]
	v_mfma_f32_16x16x32_bf16 v[24:27], v[132:135], v[204:207], v[24:27]
	v_max3_f32 v65, v65, v243, v244
	v_max3_f32 v65, v65, v245, v246
	v_max_f32_e32 v65, v65, v247
	v_cmp_lt_f32_e32 vcc, s66, v65
	s_cbranch_vccz .Lb_nr_o_1
	v_mov_b32_e32 v66, v65
	s_nop 1
	v_permlane16_swap_b32_e32 v65, v66
	v_max_f32_e32 v65, v65, v66
	v_mov_b32_e32 v66, v65
	s_nop 1
	v_permlane32_swap_b32_e32 v65, v66
	v_max_f32_e32 v65, v65, v66
	v_cmp_lt_f32_e32 vcc, s66, v65
	s_nop 1
	v_cndmask_b32_e32 v67, 0, v65, vcc
	v_sub_f32_e32 v81, 0, v67
	v_min_f32_e32 v81, 0, v81
	v_exp_f32_e32 v81, v81
	v_sub_f32_e32 v72, v72, v67
	v_sub_f32_e32 v73, v73, v67
	v_sub_f32_e32 v74, v74, v67
	v_sub_f32_e32 v75, v75, v67
	v_mul_f32_e32 v64, v64, v81
	v_mov_b32_e32 v83, v81
	s_mov_b32 s68, 1
	v_sub_f32_e32 v232, v232, v67
	v_sub_f32_e32 v233, v233, v67
	v_sub_f32_e32 v234, v234, v67
	v_sub_f32_e32 v235, v235, v67
	v_sub_f32_e32 v236, v236, v67
	v_sub_f32_e32 v237, v237, v67
	v_sub_f32_e32 v238, v238, v67
	v_sub_f32_e32 v239, v239, v67
	v_sub_f32_e32 v240, v240, v67
	v_sub_f32_e32 v241, v241, v67
	v_sub_f32_e32 v242, v242, v67
	v_sub_f32_e32 v243, v243, v67
	v_sub_f32_e32 v244, v244, v67
	v_sub_f32_e32 v245, v245, v67
	v_sub_f32_e32 v246, v246, v67
	v_sub_f32_e32 v247, v247, v67
.Lb_nr_o_1:
	v_exp_f32_e32 v232, v232
	v_exp_f32_e32 v233, v233
	v_exp_f32_e32 v234, v234
	v_exp_f32_e32 v235, v235
	v_exp_f32_e32 v236, v236
	v_exp_f32_e32 v237, v237
	s_waitcnt lgkmcnt(2)
	v_mfma_f32_16x16x32_bf16 v[56:59], v[76:79], v[188:191], v[56:59]
	v_mfma_f32_16x16x32_bf16 v[38:41], v[76:79], v[204:207], v[38:41]
	v_exp_f32_e32 v238, v238
	v_exp_f32_e32 v239, v239
	v_exp_f32_e32 v240, v240
	v_exp_f32_e32 v241, v241
	v_exp_f32_e32 v242, v242
	v_exp_f32_e32 v243, v243
	v_exp_f32_e32 v244, v244
	v_exp_f32_e32 v245, v245
	v_exp_f32_e32 v246, v246
	s_waitcnt lgkmcnt(0)
	v_mfma_f32_16x16x32_bf16 v[60:63], v[84:87], v[188:191], v[60:63]
	v_mfma_f32_16x16x32_bf16 v[28:31], v[84:87], v[204:207], v[28:31]
	v_exp_f32_e32 v247, v247
	s_cmp_eq_u32 s67, 0
	s_cbranch_scc1 .Lb_ns_o_0
	s_nop 7
	v_mul_f32_e32 v34, v34, v82
	v_mul_f32_e32 v35, v35, v82
	v_mul_f32_e32 v36, v36, v82
	v_mul_f32_e32 v37, v37, v82
	v_mul_f32_e32 v42, v42, v82
	v_mul_f32_e32 v43, v43, v82
	v_mul_f32_e32 v44, v44, v82
	v_mul_f32_e32 v45, v45, v82
	v_mul_f32_e32 v56, v56, v82
	v_mul_f32_e32 v57, v57, v82
	v_mul_f32_e32 v58, v58, v82
	v_mul_f32_e32 v59, v59, v82
	v_mul_f32_e32 v60, v60, v82
	v_mul_f32_e32 v61, v61, v82
	v_mul_f32_e32 v62, v62, v82
	v_mul_f32_e32 v63, v63, v82

.Lb_ns_o_1:
	ds_read_b128 v[248:251], v137 offset:0
	ds_read_b128 v[132:135], v137 offset:64
	ds_read_b128 v[76:79], v137 offset:2560
	s_nop 0
	v_add_f32_e32 v65, v232, v233
	v_add_f32_e32 v65, v65, v234
	ds_read_b128 v[84:87], v137 offset:2624
	s_waitcnt lgkmcnt(3)
	v_mfma_f32_16x16x32_bf16 v[88:91], v[248:251], v[16:19], v[68:71]
	v_mfma_f32_16x16x32_bf16 v[104:107], v[248:251], v[12:15], v[72:75]
	v_add_f32_e32 v65, v65, v235
	v_add_f32_e32 v65, v65, v236
	v_add_f32_e32 v65, v65, v237
	ds_read_b128 v[248:251], v137 offset:5120
	s_waitcnt lgkmcnt(3)
	v_mfma_f32_16x16x32_bf16 v[88:91], v[132:135], v[8:11], v[88:91]
	v_mfma_f32_16x16x32_bf16 v[104:107], v[132:135], v[4:7], v[104:107]
	v_add_f32_e32 v65, v65, v238
	v_add_f32_e32 v65, v65, v239
	v_add_f32_e32 v65, v65, v240
	ds_read_b128 v[132:135], v137 offset:5184
	s_waitcnt lgkmcnt(3)
	v_mfma_f32_16x16x32_bf16 v[92:95], v[76:79], v[16:19], v[68:71]
	v_mfma_f32_16x16x32_bf16 v[168:171], v[76:79], v[12:15], v[72:75]
	v_add_f32_e32 v65, v65, v241
	v_add_f32_e32 v65, v65, v242
	v_add_f32_e32 v65, v65, v243
	ds_read_b128 v[76:79], v137 offset:7680
	s_waitcnt lgkmcnt(3)
	v_mfma_f32_16x16x32_bf16 v[92:95], v[84:87], v[8:11], v[92:95]
	v_mfma_f32_16x16x32_bf16 v[168:171], v[84:87], v[4:7], v[168:171]
	v_add_f32_e32 v65, v65, v244
	v_add_f32_e32 v65, v65, v245
	v_add_f32_e32 v65, v65, v246
	ds_read_b128 v[84:87], v137 offset:7744
	s_waitcnt lgkmcnt(3)
	v_mfma_f32_16x16x32_bf16 v[96:99], v[248:251], v[16:19], v[68:71]
	v_mfma_f32_16x16x32_bf16 v[172:175], v[248:251], v[12:15], v[72:75]
	v_add_f32_e32 v65, v65, v247
	v_add_f32_e32 v64, v64, v65
	v_cvt_pk_bf16_f32 v212, v232, v233
	s_waitcnt lgkmcnt(2)
	v_mfma_f32_16x16x32_bf16 v[96:99], v[132:135], v[8:11], v[96:99]
	v_mfma_f32_16x16x32_bf16 v[172:175], v[132:135], v[4:7], v[172:175]
	v_cvt_pk_bf16_f32 v213, v234, v235
	v_cvt_pk_bf16_f32 v214, v236, v237
	v_cvt_pk_bf16_f32 v215, v238, v239
	s_waitcnt lgkmcnt(1)
	v_mfma_f32_16x16x32_bf16 v[100:103], v[76:79], v[16:19], v[68:71]
	v_mfma_f32_16x16x32_bf16 v[176:179], v[76:79], v[12:15], v[72:75]
	v_cvt_pk_bf16_f32 v52, v240, v241
	v_cvt_pk_bf16_f32 v53, v242, v243
	v_cvt_pk_bf16_f32 v54, v244, v245
	s_waitcnt lgkmcnt(0)
	v_mfma_f32_16x16x32_bf16 v[100:103], v[84:87], v[8:11], v[100:103]
	v_mfma_f32_16x16x32_bf16 v[176:179], v[84:87], v[4:7], v[176:179]
	v_cvt_pk_bf16_f32 v55, v246, v247
	s_waitcnt vmcnt(0)
	ds_write_b128 v120, v[124:127] offset:10240
	ds_write_b128 v136, v[128:131] offset:20480
	s_mov_b32 s42, s43
	s_mov_b32 s43, s51
	s_add_i32 s51, s51, 10240
	s_cmp_lg_u32 s51, 30720
	s_cselect_b32 s51, s51, 0
	s_mov_b32 s66, 0x42800000
	s_add_i32 s20, s20, 1
	s_min_u32 s8, s20, 62
	s_add_i32 s8, s8, 1
	s_mul_i32 s70, s8, 0xf8000
	s_min_u32 s8, s20, 61
	s_add_i32 s8, s8, 2
	s_mul_i32 s30, s8, 0xf8000
	s_waitcnt lgkmcnt(0)
	s_barrier
	s_cmp_lt_u32 s20, 64
	s_cbranch_scc1 .Lb_loop
	v_add_u32_e32 v122, s42, v119
	ds_read_b64_tr_b16 v[248:249], v122 offset:20480
	ds_read_b64_tr_b16 v[250:251], v122 offset:23040
	ds_read_b64_tr_b16 v[132:133], v122 offset:20512
	ds_read_b64_tr_b16 v[134:135], v122 offset:23072
	ds_read_b64_tr_b16 v[76:77], v122 offset:20544
	ds_read_b64_tr_b16 v[78:79], v122 offset:23104
	ds_read_b64_tr_b16 v[84:85], v122 offset:20576
	ds_read_b64_tr_b16 v[86:87], v122 offset:23136
	s_waitcnt lgkmcnt(6)
	v_mfma_f32_16x16x32_bf16 v[34:37], v[248:251], v[208:211], v[34:37]
	v_mfma_f32_16x16x32_bf16 v[20:23], v[248:251], v[212:215], v[20:23]
	ds_read_b64_tr_b16 v[248:249], v122 offset:25600
	ds_read_b64_tr_b16 v[250:251], v122 offset:28160
	s_waitcnt lgkmcnt(6)
	v_mfma_f32_16x16x32_bf16 v[42:45], v[132:135], v[208:211], v[42:45]
	v_mfma_f32_16x16x32_bf16 v[24:27], v[132:135], v[212:215], v[24:27]
	ds_read_b64_tr_b16 v[132:133], v122 offset:25632
	ds_read_b64_tr_b16 v[134:135], v122 offset:28192
	s_waitcnt lgkmcnt(6)
	v_mfma_f32_16x16x32_bf16 v[56:59], v[76:79], v[208:211], v[56:59]
	v_mfma_f32_16x16x32_bf16 v[38:41], v[76:79], v[212:215], v[38:41]
	ds_read_b64_tr_b16 v[76:77], v122 offset:25664
	ds_read_b64_tr_b16 v[78:79], v122 offset:28224
	s_waitcnt lgkmcnt(6)
	v_mfma_f32_16x16x32_bf16 v[60:63], v[84:87], v[208:211], v[60:63]
	v_mfma_f32_16x16x32_bf16 v[28:31], v[84:87], v[212:215], v[28:31]
	ds_read_b64_tr_b16 v[84:85], v122 offset:25696
	ds_read_b64_tr_b16 v[86:87], v122 offset:28256
	s_waitcnt lgkmcnt(6)
	v_mfma_f32_16x16x32_bf16 v[34:37], v[248:251], v[48:51], v[34:37]
	v_mfma_f32_16x16x32_bf16 v[20:23], v[248:251], v[52:55], v[20:23]
	s_waitcnt lgkmcnt(4)
	v_mfma_f32_16x16x32_bf16 v[42:45], v[132:135], v[48:51], v[42:45]
	v_mfma_f32_16x16x32_bf16 v[24:27], v[132:135], v[52:55], v[24:27]
	s_waitcnt lgkmcnt(2)
	v_mfma_f32_16x16x32_bf16 v[56:59], v[76:79], v[48:51], v[56:59]
	v_mfma_f32_16x16x32_bf16 v[38:41], v[76:79], v[52:55], v[38:41]
	s_waitcnt lgkmcnt(0)
	v_mfma_f32_16x16x32_bf16 v[60:63], v[84:87], v[48:51], v[60:63]
	v_mfma_f32_16x16x32_bf16 v[28:31], v[84:87], v[52:55], v[28:31]
